# a7 attention pipeline + DMA early issue in all 8 GEMM k-loops
# speedup vs baseline: 1.0272x; 1.0093x over previous
; #define GBAR() do { asm volatile("s_waitcnt vmcnt(0) lgkmcnt(0)" ::: "memory"); __builtin_amdgcn_s_barrier(); } while (0)
; template <int EPI, bool GUARD>
; DEVI void gemm_tile(const Params& p, const bf16_t* __restrict__ A, int lda, const bf16_t* __restrict__ Bt, int ldb, int K,
;                           int row_base, int row_lo, int row_hi, int tile_n, int layer, int which, char* lds) {
;     ...
;   const int swz = c16 >> 1;
;   int koff[2];
; #pragma unroll
;   for (int ks = 0; ks < 2; ++ks) koff[ks] = ((ks * 4 + q4) ^ swz) << 4;
;   const int arow = (wr * 64 + c16) * 128, brow = 16384 + (wc * 64 + c16) * 128;
;     ...
;   GISSUE(0, 0); GBAR();
;   for (int k0 = 0; k0 < K; k0 += 128) {
;     GISSUE(k0 + 64, 1);
;     KSTEPS(0);
;     GBAR();
;     if (k0 + 128 < K) GISSUE(k0 + 128, 0);
;     KSTEPS(1);
;     GBAR();
;   }
.LBB0_745:
	ds_read_b128 v[82:85], v64 offset:32768
	ds_read_b128 v[86:89], v107 offset:49152
	ds_read_b128 v[90:93], v64 offset:34816
	ds_read_b128 v[94:97], v107 offset:51200
	ds_read_b128 v[110:113], v107 offset:53248
	ds_read_b128 v[114:117], v107 offset:55296
	s_addk_i32 s62, 0x80
	s_waitcnt lgkmcnt(0)
	v_mfma_f32_16x16x32_bf16 v[0:3], v[82:85], v[86:89], v[0:3]
	s_add_u32 s26, s26, 0x100
	s_addc_u32 s27, s27, 0
	s_andn2_b64 vcc, exec, s[34:35]
	v_mfma_f32_16x16x32_bf16 v[4:7], v[82:85], v[94:97], v[4:7]
	v_mfma_f32_16x16x32_bf16 v[8:11], v[82:85], v[110:113], v[8:11]
	v_mfma_f32_16x16x32_bf16 v[12:15], v[82:85], v[114:117], v[12:15]
	v_mfma_f32_16x16x32_bf16 v[16:19], v[90:93], v[86:89], v[16:19]
	v_mfma_f32_16x16x32_bf16 v[20:23], v[90:93], v[94:97], v[20:23]
	v_mfma_f32_16x16x32_bf16 v[24:27], v[90:93], v[110:113], v[24:27]
	v_mfma_f32_16x16x32_bf16 v[28:31], v[90:93], v[114:117], v[28:31]
	ds_read_b128 v[82:85], v64 offset:36864
	ds_read_b128 v[90:93], v64 offset:38912
	s_waitcnt lgkmcnt(0)
	v_mfma_f32_16x16x32_bf16 v[118:121], v[82:85], v[86:89], v[32:35]
	s_nop 2
	ds_read_b128 v[32:35], v108 offset:32768
	v_mfma_f32_16x16x32_bf16 v[122:125], v[82:85], v[94:97], v[36:39]
	v_mfma_f32_16x16x32_bf16 v[126:129], v[82:85], v[110:113], v[40:43]
	v_mfma_f32_16x16x32_bf16 v[82:85], v[82:85], v[114:117], v[44:47]
	v_mfma_f32_16x16x32_bf16 v[86:89], v[90:93], v[86:89], v[48:51]
	v_mfma_f32_16x16x32_bf16 v[94:97], v[90:93], v[94:97], v[52:55]
	v_mfma_f32_16x16x32_bf16 v[110:113], v[90:93], v[110:113], v[56:59]
	v_mfma_f32_16x16x32_bf16 v[90:93], v[90:93], v[114:117], v[60:63]
	ds_read_b128 v[114:117], v109 offset:49152
	ds_read_b128 v[130:133], v108 offset:34816
	ds_read_b128 v[134:137], v109 offset:51200
	ds_read_b128 v[138:141], v109 offset:53248
	ds_read_b128 v[142:145], v109 offset:55296
	s_waitcnt lgkmcnt(0)
	v_mfma_f32_16x16x32_bf16 v[60:63], v[32:35], v[114:117], v[0:3]
	v_mfma_f32_16x16x32_bf16 v[52:55], v[32:35], v[138:141], v[8:11]
	s_nop 1
	ds_read_b128 v[0:3], v108 offset:36864
	ds_read_b128 v[8:11], v108 offset:38912
	s_waitcnt vmcnt(0) lgkmcnt(0)
	s_barrier
	s_cbranch_vccz .Lge2_exit1
	v_mfma_f32_16x16x32_bf16 v[56:59], v[32:35], v[134:137], v[4:7]
	s_mov_b32 m0, s63
	v_lshl_add_u64 v[246:247], s[26:27], 0, v[66:67]
	v_lshl_add_u64 v[246:247], v[246:247], 0, s[4:5]
	global_load_lds_dwordx4 v[246:247], off
	v_mfma_f32_16x16x32_bf16 v[48:51], v[32:35], v[142:145], v[12:15]
	s_mov_b32 m0, s72
	v_lshl_add_u64 v[246:247], s[26:27], 0, v[74:75]
	v_lshl_add_u64 v[246:247], v[246:247], 0, s[6:7]
	global_load_lds_dwordx4 v[246:247], off
	v_mfma_f32_16x16x32_bf16 v[44:47], v[130:133], v[114:117], v[16:19]
	s_mov_b32 m0, s68
	v_lshl_add_u64 v[246:247], s[26:27], 0, v[68:69]
	v_lshl_add_u64 v[246:247], v[246:247], 0, s[4:5]
	global_load_lds_dwordx4 v[246:247], off
	v_mfma_f32_16x16x32_bf16 v[40:43], v[130:133], v[134:137], v[20:23]
	s_mov_b32 m0, s69
	v_lshl_add_u64 v[246:247], s[26:27], 0, v[76:77]
	v_lshl_add_u64 v[246:247], v[246:247], 0, s[6:7]
	global_load_lds_dwordx4 v[246:247], off
	v_mfma_f32_16x16x32_bf16 v[36:39], v[130:133], v[138:141], v[24:27]
	s_mov_b32 m0, s70
	v_lshl_add_u64 v[246:247], s[26:27], 0, v[70:71]
	v_lshl_add_u64 v[246:247], v[246:247], 0, s[4:5]
	global_load_lds_dwordx4 v[246:247], off
	v_mfma_f32_16x16x32_bf16 v[32:35], v[130:133], v[142:145], v[28:31]
	s_mov_b32 m0, s71
	v_lshl_add_u64 v[246:247], s[26:27], 0, v[78:79]
	v_lshl_add_u64 v[246:247], v[246:247], 0, s[6:7]
	global_load_lds_dwordx4 v[246:247], off
	s_waitcnt lgkmcnt(0)
	v_mfma_f32_16x16x32_bf16 v[28:31], v[0:3], v[114:117], v[118:121]
	s_mov_b32 m0, s73
	v_lshl_add_u64 v[246:247], s[26:27], 0, v[72:73]
	v_lshl_add_u64 v[246:247], v[246:247], 0, s[4:5]
	global_load_lds_dwordx4 v[246:247], off
	v_mfma_f32_16x16x32_bf16 v[24:27], v[0:3], v[134:137], v[122:125]
	s_mov_b32 m0, s74
	v_lshl_add_u64 v[246:247], s[26:27], 0, v[80:81]
	v_lshl_add_u64 v[246:247], v[246:247], 0, s[6:7]
	global_load_lds_dwordx4 v[246:247], off
	v_mfma_f32_16x16x32_bf16 v[16:19], v[0:3], v[138:141], v[126:129]
	v_mfma_f32_16x16x32_bf16 v[12:15], v[0:3], v[142:145], v[82:85]
	v_mfma_f32_16x16x32_bf16 v[4:7], v[8:11], v[114:117], v[86:89]
	v_mfma_f32_16x16x32_bf16 v[0:3], v[8:11], v[134:137], v[94:97]
	v_mfma_f32_16x16x32_bf16 v[20:23], v[8:11], v[138:141], v[110:113]
	v_mfma_f32_16x16x32_bf16 v[8:11], v[8:11], v[142:145], v[90:93]
	s_cmpk_gt_u32 s62, 0xa7f
	s_cselect_b64 s[34:35], -1, 0
	s_and_b64 vcc, exec, s[34:35]
	s_branch .Lge2_k0
.Lge2_exit1:
	v_mfma_f32_16x16x32_bf16 v[56:59], v[32:35], v[134:137], v[4:7]
	v_mfma_f32_16x16x32_bf16 v[48:51], v[32:35], v[142:145], v[12:15]
	v_mfma_f32_16x16x32_bf16 v[44:47], v[130:133], v[114:117], v[16:19]
	v_mfma_f32_16x16x32_bf16 v[40:43], v[130:133], v[134:137], v[20:23]
	v_mfma_f32_16x16x32_bf16 v[36:39], v[130:133], v[138:141], v[24:27]
	v_mfma_f32_16x16x32_bf16 v[32:35], v[130:133], v[142:145], v[28:31]
	s_waitcnt lgkmcnt(0)
	v_mfma_f32_16x16x32_bf16 v[28:31], v[0:3], v[114:117], v[118:121]
	v_mfma_f32_16x16x32_bf16 v[24:27], v[0:3], v[134:137], v[122:125]
	v_mfma_f32_16x16x32_bf16 v[16:19], v[0:3], v[138:141], v[126:129]
	v_mfma_f32_16x16x32_bf16 v[12:15], v[0:3], v[142:145], v[82:85]
	v_mfma_f32_16x16x32_bf16 v[4:7], v[8:11], v[114:117], v[86:89]
	v_mfma_f32_16x16x32_bf16 v[0:3], v[8:11], v[134:137], v[94:97]
	v_mfma_f32_16x16x32_bf16 v[20:23], v[8:11], v[138:141], v[110:113]
	v_mfma_f32_16x16x32_bf16 v[8:11], v[8:11], v[142:145], v[90:93]
	s_branch .LBB0_735

; #define GBAR() do { asm volatile("s_waitcnt vmcnt(0) lgkmcnt(0)" ::: "memory"); __builtin_amdgcn_s_barrier(); } while (0)
; template <int EPI, bool GUARD>
; DEVI void gemm_tile(const Params& p, const bf16_t* __restrict__ A, int lda, const bf16_t* __restrict__ Bt, int ldb, int K,
;                           int row_base, int row_lo, int row_hi, int tile_n, int layer, int which, char* lds) {
;     ...
;   const int swz = c16 >> 1;
;   int koff[2];
; #pragma unroll
;   for (int ks = 0; ks < 2; ++ks) koff[ks] = ((ks * 4 + q4) ^ swz) << 4;
;   const int arow = (wr * 64 + c16) * 128, brow = 16384 + (wc * 64 + c16) * 128;
;     ...
;   GISSUE(0, 0); GBAR();
;   for (int k0 = 0; k0 < K; k0 += 128) {
;     GISSUE(k0 + 64, 1);
;     KSTEPS(0);
;     GBAR();
;     if (k0 + 128 < K) GISSUE(k0 + 128, 0);
;     KSTEPS(1);
;     GBAR();
;   }
.Lge2_k0:
	ds_read_b128 v[110:113], v64
	ds_read_b128 v[114:117], v107 offset:16384
	ds_read_b128 v[118:121], v64 offset:2048
	ds_read_b128 v[122:125], v107 offset:18432
	ds_read_b128 v[126:129], v107 offset:20480
	ds_read_b128 v[130:133], v107 offset:22528
	s_waitcnt lgkmcnt(0)
	v_mfma_f32_16x16x32_bf16 v[60:63], v[110:113], v[114:117], v[60:63]
	v_mfma_f32_16x16x32_bf16 v[56:59], v[110:113], v[122:125], v[56:59]
	v_mfma_f32_16x16x32_bf16 v[52:55], v[110:113], v[126:129], v[52:55]
	v_mfma_f32_16x16x32_bf16 v[48:51], v[110:113], v[130:133], v[48:51]
	v_mfma_f32_16x16x32_bf16 v[44:47], v[118:121], v[114:117], v[44:47]
	v_mfma_f32_16x16x32_bf16 v[40:43], v[118:121], v[122:125], v[40:43]
	v_mfma_f32_16x16x32_bf16 v[36:39], v[118:121], v[126:129], v[36:39]
	v_mfma_f32_16x16x32_bf16 v[32:35], v[118:121], v[130:133], v[32:35]
	ds_read_b128 v[110:113], v64 offset:4096
	ds_read_b128 v[118:121], v64 offset:6144
	s_waitcnt lgkmcnt(0)
	v_mfma_f32_16x16x32_bf16 v[134:137], v[110:113], v[114:117], v[28:31]
	v_mfma_f32_16x16x32_bf16 v[138:141], v[110:113], v[122:125], v[24:27]
	v_mfma_f32_16x16x32_bf16 v[142:145], v[110:113], v[126:129], v[16:19]
	v_mfma_f32_16x16x32_bf16 v[110:113], v[110:113], v[130:133], v[12:15]
	s_nop 2
	ds_read_b128 v[12:15], v108
	v_mfma_f32_16x16x32_bf16 v[114:117], v[118:121], v[114:117], v[4:7]
	v_mfma_f32_16x16x32_bf16 v[122:125], v[118:121], v[122:125], v[0:3]
	v_mfma_f32_16x16x32_bf16 v[126:129], v[118:121], v[126:129], v[20:23]
	v_mfma_f32_16x16x32_bf16 v[118:121], v[118:121], v[130:133], v[8:11]
	ds_read_b128 v[130:133], v109 offset:16384
	ds_read_b128 v[28:31], v108 offset:2048
	ds_read_b128 v[146:149], v109 offset:18432
	s_waitcnt lgkmcnt(0)
	v_mfma_f32_16x16x32_bf16 v[0:3], v[12:15], v[130:133], v[60:63]
	v_mfma_f32_16x16x32_bf16 v[4:7], v[12:15], v[146:149], v[56:59]
	s_nop 2
	ds_read_b128 v[56:59], v109 offset:20480
	ds_read_b128 v[60:63], v109 offset:22528
	v_mfma_f32_16x16x32_bf16 v[16:19], v[28:31], v[130:133], v[44:47]
	s_nop 2
	ds_read_b128 v[44:47], v108 offset:4096
	ds_read_b128 v[150:153], v108 offset:6144
	s_waitcnt vmcnt(0) lgkmcnt(0)
	s_barrier
	s_cbranch_vccnz .Lge2_last0
	s_waitcnt lgkmcnt(0)
	v_mfma_f32_16x16x32_bf16 v[8:11], v[12:15], v[56:59], v[52:55]
	s_mov_b32 m0, s54
	v_lshl_add_u64 v[246:247], s[26:27], 0, v[66:67]
	v_lshl_add_u64 v[246:247], v[246:247], 0, s[8:9]
	global_load_lds_dwordx4 v[246:247], off
	v_mfma_f32_16x16x32_bf16 v[12:15], v[12:15], v[60:63], v[48:51]
	s_mov_b32 m0, s55
	v_lshl_add_u64 v[246:247], s[26:27], 0, v[74:75]
	v_lshl_add_u64 v[246:247], v[246:247], 0, s[16:17]
	global_load_lds_dwordx4 v[246:247], off
	v_mfma_f32_16x16x32_bf16 v[20:23], v[28:31], v[146:149], v[40:43]
	s_mov_b32 m0, s56
	v_lshl_add_u64 v[246:247], s[26:27], 0, v[68:69]
	v_lshl_add_u64 v[246:247], v[246:247], 0, s[8:9]
	global_load_lds_dwordx4 v[246:247], off
	v_mfma_f32_16x16x32_bf16 v[24:27], v[28:31], v[56:59], v[36:39]
	s_mov_b32 m0, s57
	v_lshl_add_u64 v[246:247], s[26:27], 0, v[76:77]
	v_lshl_add_u64 v[246:247], v[246:247], 0, s[16:17]
	global_load_lds_dwordx4 v[246:247], off
	v_mfma_f32_16x16x32_bf16 v[28:31], v[28:31], v[60:63], v[32:35]
	s_mov_b32 m0, s58
	v_lshl_add_u64 v[246:247], s[26:27], 0, v[70:71]
	v_lshl_add_u64 v[246:247], v[246:247], 0, s[8:9]
	global_load_lds_dwordx4 v[246:247], off
	v_mfma_f32_16x16x32_bf16 v[32:35], v[44:47], v[130:133], v[134:137]
	s_mov_b32 m0, s59
	v_lshl_add_u64 v[246:247], s[26:27], 0, v[78:79]
	v_lshl_add_u64 v[246:247], v[246:247], 0, s[16:17]
	global_load_lds_dwordx4 v[246:247], off
	v_mfma_f32_16x16x32_bf16 v[36:39], v[44:47], v[146:149], v[138:141]
	s_mov_b32 m0, s60
	v_lshl_add_u64 v[246:247], s[26:27], 0, v[72:73]
	v_lshl_add_u64 v[246:247], v[246:247], 0, s[8:9]
	global_load_lds_dwordx4 v[246:247], off
	v_mfma_f32_16x16x32_bf16 v[40:43], v[44:47], v[56:59], v[142:145]
	s_mov_b32 m0, s61
	v_lshl_add_u64 v[246:247], s[26:27], 0, v[80:81]
	v_lshl_add_u64 v[246:247], v[246:247], 0, s[16:17]
	global_load_lds_dwordx4 v[246:247], off
	v_mfma_f32_16x16x32_bf16 v[44:47], v[44:47], v[60:63], v[110:113]
	v_mfma_f32_16x16x32_bf16 v[48:51], v[150:153], v[130:133], v[114:117]
	v_mfma_f32_16x16x32_bf16 v[52:55], v[150:153], v[146:149], v[122:125]
	v_mfma_f32_16x16x32_bf16 v[56:59], v[150:153], v[56:59], v[126:129]
	v_mfma_f32_16x16x32_bf16 v[60:63], v[150:153], v[60:63], v[118:121]
	s_branch .LBB0_745
.Lge2_last0:
	s_waitcnt lgkmcnt(0)
	v_mfma_f32_16x16x32_bf16 v[8:11], v[12:15], v[56:59], v[52:55]
	v_mfma_f32_16x16x32_bf16 v[12:15], v[12:15], v[60:63], v[48:51]
	v_mfma_f32_16x16x32_bf16 v[20:23], v[28:31], v[146:149], v[40:43]
	v_mfma_f32_16x16x32_bf16 v[24:27], v[28:31], v[56:59], v[36:39]
	v_mfma_f32_16x16x32_bf16 v[28:31], v[28:31], v[60:63], v[32:35]
	v_mfma_f32_16x16x32_bf16 v[32:35], v[44:47], v[130:133], v[134:137]
	v_mfma_f32_16x16x32_bf16 v[36:39], v[44:47], v[146:149], v[138:141]
	v_mfma_f32_16x16x32_bf16 v[40:43], v[44:47], v[56:59], v[142:145]
	v_mfma_f32_16x16x32_bf16 v[44:47], v[44:47], v[60:63], v[110:113]
	v_mfma_f32_16x16x32_bf16 v[48:51], v[150:153], v[130:133], v[114:117]
	v_mfma_f32_16x16x32_bf16 v[52:55], v[150:153], v[146:149], v[122:125]
	v_mfma_f32_16x16x32_bf16 v[56:59], v[150:153], v[56:59], v[126:129]
	v_mfma_f32_16x16x32_bf16 v[60:63], v[150:153], v[60:63], v[118:121]
	s_branch .LBB0_745

; #define GBAR() do { asm volatile("s_waitcnt vmcnt(0) lgkmcnt(0)" ::: "memory"); __builtin_amdgcn_s_barrier(); } while (0)
; template <int EPI, bool GUARD>
; DEVI void gemm_tile(const Params& p, const bf16_t* __restrict__ A, int lda, const bf16_t* __restrict__ Bt, int ldb, int K,
;                           int row_base, int row_lo, int row_hi, int tile_n, int layer, int which, char* lds) {
;     ...
;   const int swz = c16 >> 1;
;   int koff[2];
; #pragma unroll
;   for (int ks = 0; ks < 2; ++ks) koff[ks] = ((ks * 4 + q4) ^ swz) << 4;
;   const int arow = (wr * 64 + c16) * 128, brow = 16384 + (wc * 64 + c16) * 128;
;     ...
;   GISSUE(0, 0); GBAR();
;   for (int k0 = 0; k0 < K; k0 += 128) {
;     GISSUE(k0 + 64, 1);
;     KSTEPS(0);
;     GBAR();
;     if (k0 + 128 < K) GISSUE(k0 + 128, 0);
;     KSTEPS(1);
;     GBAR();
;   }
.LBB0_1131:
	ds_read_b128 v[82:85], v64 offset:32768
	ds_read_b128 v[86:89], v107 offset:49152
	ds_read_b128 v[90:93], v64 offset:34816
	ds_read_b128 v[94:97], v107 offset:51200
	ds_read_b128 v[110:113], v107 offset:53248
	ds_read_b128 v[114:117], v107 offset:55296
	s_addk_i32 s52, 0x80
	s_waitcnt lgkmcnt(0)
	v_mfma_f32_16x16x32_bf16 v[0:3], v[82:85], v[86:89], v[0:3]
	s_add_u32 s18, s18, 0x100
	s_addc_u32 s19, s19, 0
	s_andn2_b64 vcc, exec, s[26:27]
	v_mfma_f32_16x16x32_bf16 v[4:7], v[82:85], v[94:97], v[4:7]
	v_mfma_f32_16x16x32_bf16 v[8:11], v[82:85], v[110:113], v[8:11]
	v_mfma_f32_16x16x32_bf16 v[12:15], v[82:85], v[114:117], v[12:15]
	v_mfma_f32_16x16x32_bf16 v[16:19], v[90:93], v[86:89], v[16:19]
	v_mfma_f32_16x16x32_bf16 v[20:23], v[90:93], v[94:97], v[20:23]
	v_mfma_f32_16x16x32_bf16 v[24:27], v[90:93], v[110:113], v[24:27]
	v_mfma_f32_16x16x32_bf16 v[28:31], v[90:93], v[114:117], v[28:31]
	ds_read_b128 v[82:85], v64 offset:36864
	ds_read_b128 v[90:93], v64 offset:38912
	s_waitcnt lgkmcnt(0)
	v_mfma_f32_16x16x32_bf16 v[118:121], v[82:85], v[86:89], v[32:35]
	s_nop 2
	ds_read_b128 v[32:35], v108 offset:32768
	v_mfma_f32_16x16x32_bf16 v[122:125], v[82:85], v[94:97], v[36:39]
	v_mfma_f32_16x16x32_bf16 v[126:129], v[82:85], v[110:113], v[40:43]
	v_mfma_f32_16x16x32_bf16 v[82:85], v[82:85], v[114:117], v[44:47]
	v_mfma_f32_16x16x32_bf16 v[86:89], v[90:93], v[86:89], v[48:51]
	v_mfma_f32_16x16x32_bf16 v[94:97], v[90:93], v[94:97], v[52:55]
	v_mfma_f32_16x16x32_bf16 v[110:113], v[90:93], v[110:113], v[56:59]
	v_mfma_f32_16x16x32_bf16 v[90:93], v[90:93], v[114:117], v[60:63]
	ds_read_b128 v[114:117], v109 offset:49152
	ds_read_b128 v[130:133], v108 offset:34816
	ds_read_b128 v[134:137], v109 offset:51200
	ds_read_b128 v[138:141], v109 offset:53248
	ds_read_b128 v[142:145], v109 offset:55296
	s_waitcnt lgkmcnt(0)
	v_mfma_f32_16x16x32_bf16 v[60:63], v[32:35], v[114:117], v[0:3]
	v_mfma_f32_16x16x32_bf16 v[52:55], v[32:35], v[138:141], v[8:11]
	s_nop 1
	ds_read_b128 v[0:3], v108 offset:36864
	ds_read_b128 v[8:11], v108 offset:38912
	s_waitcnt vmcnt(0) lgkmcnt(0)
	s_barrier
	s_cbranch_vccz .Lge5_exit1
	v_mfma_f32_16x16x32_bf16 v[56:59], v[32:35], v[134:137], v[4:7]
	s_mov_b32 m0, s53
	v_lshl_add_u64 v[246:247], s[18:19], 0, v[66:67]
	v_lshl_add_u64 v[246:247], v[246:247], 0, s[2:3]
	global_load_lds_dwordx4 v[246:247], off
	v_mfma_f32_16x16x32_bf16 v[48:51], v[32:35], v[142:145], v[12:15]
	s_mov_b32 m0, s57
	v_lshl_add_u64 v[246:247], s[18:19], 0, v[74:75]
	v_lshl_add_u64 v[246:247], v[246:247], 0, s[4:5]
	global_load_lds_dwordx4 v[246:247], off
	v_mfma_f32_16x16x32_bf16 v[44:47], v[130:133], v[114:117], v[16:19]
	s_mov_b32 m0, s54
	v_lshl_add_u64 v[246:247], s[18:19], 0, v[68:69]
	v_lshl_add_u64 v[246:247], v[246:247], 0, s[2:3]
	global_load_lds_dwordx4 v[246:247], off
	v_mfma_f32_16x16x32_bf16 v[40:43], v[130:133], v[134:137], v[20:23]
	s_mov_b32 m0, s55
	v_lshl_add_u64 v[246:247], s[18:19], 0, v[76:77]
	v_lshl_add_u64 v[246:247], v[246:247], 0, s[4:5]
	global_load_lds_dwordx4 v[246:247], off
	v_mfma_f32_16x16x32_bf16 v[36:39], v[130:133], v[138:141], v[24:27]
	s_mov_b32 m0, s58
	v_lshl_add_u64 v[246:247], s[18:19], 0, v[70:71]
	v_lshl_add_u64 v[246:247], v[246:247], 0, s[2:3]
	global_load_lds_dwordx4 v[246:247], off
	v_mfma_f32_16x16x32_bf16 v[32:35], v[130:133], v[142:145], v[28:31]
	s_mov_b32 m0, s56
	v_lshl_add_u64 v[246:247], s[18:19], 0, v[78:79]
	v_lshl_add_u64 v[246:247], v[246:247], 0, s[4:5]
	global_load_lds_dwordx4 v[246:247], off
	s_waitcnt lgkmcnt(0)
	v_mfma_f32_16x16x32_bf16 v[28:31], v[0:3], v[114:117], v[118:121]
	s_mov_b32 m0, s59
	v_lshl_add_u64 v[246:247], s[18:19], 0, v[72:73]
	v_lshl_add_u64 v[246:247], v[246:247], 0, s[2:3]
	global_load_lds_dwordx4 v[246:247], off
	v_mfma_f32_16x16x32_bf16 v[24:27], v[0:3], v[134:137], v[122:125]
	s_mov_b32 m0, s60
	v_lshl_add_u64 v[246:247], s[18:19], 0, v[80:81]
	v_lshl_add_u64 v[246:247], v[246:247], 0, s[4:5]
	global_load_lds_dwordx4 v[246:247], off
	v_mfma_f32_16x16x32_bf16 v[16:19], v[0:3], v[138:141], v[126:129]
	v_mfma_f32_16x16x32_bf16 v[12:15], v[0:3], v[142:145], v[82:85]
	v_mfma_f32_16x16x32_bf16 v[4:7], v[8:11], v[114:117], v[86:89]
	v_mfma_f32_16x16x32_bf16 v[0:3], v[8:11], v[134:137], v[94:97]
	v_mfma_f32_16x16x32_bf16 v[20:23], v[8:11], v[138:141], v[110:113]
	v_mfma_f32_16x16x32_bf16 v[8:11], v[8:11], v[142:145], v[90:93]
	s_cmpk_gt_u32 s52, 0x37f
	s_cselect_b64 s[26:27], -1, 0
	s_and_b64 vcc, exec, s[26:27]
	s_branch .Lge5_k0

; #define GBAR() do { asm volatile("s_waitcnt vmcnt(0) lgkmcnt(0)" ::: "memory"); __builtin_amdgcn_s_barrier(); } while (0)
; template <int EPI, bool GUARD>
; DEVI void gemm_tile(const Params& p, const bf16_t* __restrict__ A, int lda, const bf16_t* __restrict__ Bt, int ldb, int K,
;                           int row_base, int row_lo, int row_hi, int tile_n, int layer, int which, char* lds) {
;     ...
;   const int swz = c16 >> 1;
;   int koff[2];
; #pragma unroll
;   for (int ks = 0; ks < 2; ++ks) koff[ks] = ((ks * 4 + q4) ^ swz) << 4;
;   const int arow = (wr * 64 + c16) * 128, brow = 16384 + (wc * 64 + c16) * 128;
;     ...
;   GISSUE(0, 0); GBAR();
;   for (int k0 = 0; k0 < K; k0 += 128) {
;     GISSUE(k0 + 64, 1);
;     KSTEPS(0);
;     GBAR();
;     if (k0 + 128 < K) GISSUE(k0 + 128, 0);
;     KSTEPS(1);
;     GBAR();
;   }
.Lge5_k0:
	ds_read_b128 v[110:113], v64
	ds_read_b128 v[114:117], v107 offset:16384
	ds_read_b128 v[118:121], v64 offset:2048
	ds_read_b128 v[122:125], v107 offset:18432
	ds_read_b128 v[126:129], v107 offset:20480
	ds_read_b128 v[130:133], v107 offset:22528
	s_waitcnt lgkmcnt(0)
	v_mfma_f32_16x16x32_bf16 v[60:63], v[110:113], v[114:117], v[60:63]
	v_mfma_f32_16x16x32_bf16 v[56:59], v[110:113], v[122:125], v[56:59]
	v_mfma_f32_16x16x32_bf16 v[52:55], v[110:113], v[126:129], v[52:55]
	v_mfma_f32_16x16x32_bf16 v[48:51], v[110:113], v[130:133], v[48:51]
	v_mfma_f32_16x16x32_bf16 v[44:47], v[118:121], v[114:117], v[44:47]
	v_mfma_f32_16x16x32_bf16 v[40:43], v[118:121], v[122:125], v[40:43]
	v_mfma_f32_16x16x32_bf16 v[36:39], v[118:121], v[126:129], v[36:39]
	v_mfma_f32_16x16x32_bf16 v[32:35], v[118:121], v[130:133], v[32:35]
	ds_read_b128 v[110:113], v64 offset:4096
	ds_read_b128 v[118:121], v64 offset:6144
	s_waitcnt lgkmcnt(0)
	v_mfma_f32_16x16x32_bf16 v[134:137], v[110:113], v[114:117], v[28:31]
	v_mfma_f32_16x16x32_bf16 v[138:141], v[110:113], v[122:125], v[24:27]
	v_mfma_f32_16x16x32_bf16 v[142:145], v[110:113], v[126:129], v[16:19]
	v_mfma_f32_16x16x32_bf16 v[110:113], v[110:113], v[130:133], v[12:15]
	s_nop 2
	ds_read_b128 v[12:15], v108
	v_mfma_f32_16x16x32_bf16 v[114:117], v[118:121], v[114:117], v[4:7]
	v_mfma_f32_16x16x32_bf16 v[122:125], v[118:121], v[122:125], v[0:3]
	v_mfma_f32_16x16x32_bf16 v[126:129], v[118:121], v[126:129], v[20:23]
	v_mfma_f32_16x16x32_bf16 v[118:121], v[118:121], v[130:133], v[8:11]
	ds_read_b128 v[130:133], v109 offset:16384
	ds_read_b128 v[28:31], v108 offset:2048
	ds_read_b128 v[146:149], v109 offset:18432
	s_waitcnt lgkmcnt(0)
	v_mfma_f32_16x16x32_bf16 v[0:3], v[12:15], v[130:133], v[60:63]
	v_mfma_f32_16x16x32_bf16 v[4:7], v[12:15], v[146:149], v[56:59]
	s_nop 2
	ds_read_b128 v[56:59], v109 offset:20480
	ds_read_b128 v[60:63], v109 offset:22528
	v_mfma_f32_16x16x32_bf16 v[16:19], v[28:31], v[130:133], v[44:47]
	s_nop 2
	ds_read_b128 v[44:47], v108 offset:4096
	ds_read_b128 v[150:153], v108 offset:6144
	s_waitcnt vmcnt(0) lgkmcnt(0)
	s_barrier
	s_cbranch_vccnz .Lge5_last0
	s_waitcnt lgkmcnt(0)
	v_mfma_f32_16x16x32_bf16 v[8:11], v[12:15], v[56:59], v[52:55]
	s_mov_b32 m0, s40
	v_lshl_add_u64 v[246:247], s[18:19], 0, v[66:67]
	v_lshl_add_u64 v[246:247], v[246:247], 0, s[6:7]
	global_load_lds_dwordx4 v[246:247], off
	v_mfma_f32_16x16x32_bf16 v[12:15], v[12:15], v[60:63], v[48:51]
	s_mov_b32 m0, s41
	v_lshl_add_u64 v[246:247], s[18:19], 0, v[74:75]
	v_lshl_add_u64 v[246:247], v[246:247], 0, s[8:9]
	global_load_lds_dwordx4 v[246:247], off
	v_mfma_f32_16x16x32_bf16 v[20:23], v[28:31], v[146:149], v[40:43]
	s_mov_b32 m0, s42
	v_lshl_add_u64 v[246:247], s[18:19], 0, v[68:69]
	v_lshl_add_u64 v[246:247], v[246:247], 0, s[6:7]
	global_load_lds_dwordx4 v[246:247], off
	v_mfma_f32_16x16x32_bf16 v[24:27], v[28:31], v[56:59], v[36:39]
	s_mov_b32 m0, s43
	v_lshl_add_u64 v[246:247], s[18:19], 0, v[76:77]
	v_lshl_add_u64 v[246:247], v[246:247], 0, s[8:9]
	global_load_lds_dwordx4 v[246:247], off
	v_mfma_f32_16x16x32_bf16 v[28:31], v[28:31], v[60:63], v[32:35]
	s_mov_b32 m0, s44
	v_lshl_add_u64 v[246:247], s[18:19], 0, v[70:71]
	v_lshl_add_u64 v[246:247], v[246:247], 0, s[6:7]
	global_load_lds_dwordx4 v[246:247], off
	v_mfma_f32_16x16x32_bf16 v[32:35], v[44:47], v[130:133], v[134:137]
	s_mov_b32 m0, s45
	v_lshl_add_u64 v[246:247], s[18:19], 0, v[78:79]
	v_lshl_add_u64 v[246:247], v[246:247], 0, s[8:9]
	global_load_lds_dwordx4 v[246:247], off
	v_mfma_f32_16x16x32_bf16 v[36:39], v[44:47], v[146:149], v[138:141]
	s_mov_b32 m0, s46
	v_lshl_add_u64 v[246:247], s[18:19], 0, v[72:73]
	v_lshl_add_u64 v[246:247], v[246:247], 0, s[6:7]
	global_load_lds_dwordx4 v[246:247], off
	v_mfma_f32_16x16x32_bf16 v[40:43], v[44:47], v[56:59], v[142:145]
	s_mov_b32 m0, s47
	v_lshl_add_u64 v[246:247], s[18:19], 0, v[80:81]
	v_lshl_add_u64 v[246:247], v[246:247], 0, s[8:9]
	global_load_lds_dwordx4 v[246:247], off
	v_mfma_f32_16x16x32_bf16 v[44:47], v[44:47], v[60:63], v[110:113]
	v_mfma_f32_16x16x32_bf16 v[48:51], v[150:153], v[130:133], v[114:117]
	v_mfma_f32_16x16x32_bf16 v[52:55], v[150:153], v[146:149], v[122:125]
	v_mfma_f32_16x16x32_bf16 v[56:59], v[150:153], v[56:59], v[126:129]
	v_mfma_f32_16x16x32_bf16 v[60:63], v[150:153], v[60:63], v[118:121]
	s_branch .LBB0_1131

; #define GBAR() do { asm volatile("s_waitcnt vmcnt(0) lgkmcnt(0)" ::: "memory"); __builtin_amdgcn_s_barrier(); } while (0)
; template <int EPI, bool GUARD>
; DEVI void gemm_tile(const Params& p, const bf16_t* __restrict__ A, int lda, const bf16_t* __restrict__ Bt, int ldb, int K,
;                           int row_base, int row_lo, int row_hi, int tile_n, int layer, int which, char* lds) {
;     ...
;   const int swz = c16 >> 1;
;   int koff[2];
; #pragma unroll
;   for (int ks = 0; ks < 2; ++ks) koff[ks] = ((ks * 4 + q4) ^ swz) << 4;
;   const int arow = (wr * 64 + c16) * 128, brow = 16384 + (wc * 64 + c16) * 128;
;     ...
;   GISSUE(0, 0); GBAR();
;   for (int k0 = 0; k0 < K; k0 += 128) {
;     GISSUE(k0 + 64, 1);
;     KSTEPS(0);
;     GBAR();
;     if (k0 + 128 < K) GISSUE(k0 + 128, 0);
;     KSTEPS(1);
;     GBAR();
;   }
.LBB0_1336:
	ds_read_b128 v[82:85], v64 offset:32768
	ds_read_b128 v[86:89], v107 offset:49152
	ds_read_b128 v[90:93], v64 offset:34816
	ds_read_b128 v[94:97], v107 offset:51200
	ds_read_b128 v[110:113], v107 offset:53248
	ds_read_b128 v[114:117], v107 offset:55296
	s_addk_i32 s44, 0x80
	s_waitcnt lgkmcnt(0)
	v_mfma_f32_16x16x32_bf16 v[0:3], v[82:85], v[86:89], v[0:3]
	s_add_u32 s18, s18, 0x100
	s_addc_u32 s19, s19, 0
	s_andn2_b64 vcc, exec, s[20:21]
	v_mfma_f32_16x16x32_bf16 v[4:7], v[82:85], v[94:97], v[4:7]
	v_mfma_f32_16x16x32_bf16 v[8:11], v[82:85], v[110:113], v[8:11]
	v_mfma_f32_16x16x32_bf16 v[12:15], v[82:85], v[114:117], v[12:15]
	v_mfma_f32_16x16x32_bf16 v[16:19], v[90:93], v[86:89], v[16:19]
	v_mfma_f32_16x16x32_bf16 v[20:23], v[90:93], v[94:97], v[20:23]
	v_mfma_f32_16x16x32_bf16 v[24:27], v[90:93], v[110:113], v[24:27]
	v_mfma_f32_16x16x32_bf16 v[28:31], v[90:93], v[114:117], v[28:31]
	ds_read_b128 v[82:85], v64 offset:36864
	ds_read_b128 v[90:93], v64 offset:38912
	s_waitcnt lgkmcnt(0)
	v_mfma_f32_16x16x32_bf16 v[118:121], v[82:85], v[86:89], v[32:35]
	s_nop 2
	ds_read_b128 v[32:35], v108 offset:32768
	v_mfma_f32_16x16x32_bf16 v[122:125], v[82:85], v[94:97], v[36:39]
	v_mfma_f32_16x16x32_bf16 v[126:129], v[82:85], v[110:113], v[40:43]
	v_mfma_f32_16x16x32_bf16 v[82:85], v[82:85], v[114:117], v[44:47]
	v_mfma_f32_16x16x32_bf16 v[86:89], v[90:93], v[86:89], v[48:51]
	v_mfma_f32_16x16x32_bf16 v[94:97], v[90:93], v[94:97], v[52:55]
	v_mfma_f32_16x16x32_bf16 v[110:113], v[90:93], v[110:113], v[56:59]
	v_mfma_f32_16x16x32_bf16 v[90:93], v[90:93], v[114:117], v[60:63]
	ds_read_b128 v[114:117], v109 offset:49152
	ds_read_b128 v[130:133], v108 offset:34816
	ds_read_b128 v[134:137], v109 offset:51200
	ds_read_b128 v[138:141], v109 offset:53248
	ds_read_b128 v[142:145], v109 offset:55296
	s_waitcnt lgkmcnt(0)
	v_mfma_f32_16x16x32_bf16 v[60:63], v[32:35], v[114:117], v[0:3]
	v_mfma_f32_16x16x32_bf16 v[52:55], v[32:35], v[138:141], v[8:11]
	s_nop 1
	ds_read_b128 v[0:3], v108 offset:36864
	ds_read_b128 v[8:11], v108 offset:38912
	s_waitcnt vmcnt(0) lgkmcnt(0)
	s_barrier
	s_cbranch_vccz .Lge7_exit1
	v_mfma_f32_16x16x32_bf16 v[56:59], v[32:35], v[134:137], v[4:7]
	s_mov_b32 m0, s45
	v_lshl_add_u64 v[246:247], s[18:19], 0, v[66:67]
	v_lshl_add_u64 v[246:247], v[246:247], 0, s[2:3]
	global_load_lds_dwordx4 v[246:247], off
	v_mfma_f32_16x16x32_bf16 v[48:51], v[32:35], v[142:145], v[12:15]
	s_mov_b32 m0, s50
	v_lshl_add_u64 v[246:247], s[18:19], 0, v[74:75]
	v_lshl_add_u64 v[246:247], v[246:247], 0, s[4:5]
	global_load_lds_dwordx4 v[246:247], off
	v_mfma_f32_16x16x32_bf16 v[44:47], v[130:133], v[114:117], v[16:19]
	s_mov_b32 m0, s46
	v_lshl_add_u64 v[246:247], s[18:19], 0, v[68:69]
	v_lshl_add_u64 v[246:247], v[246:247], 0, s[2:3]
	global_load_lds_dwordx4 v[246:247], off
	v_mfma_f32_16x16x32_bf16 v[40:43], v[130:133], v[134:137], v[20:23]
	s_mov_b32 m0, s47
	v_lshl_add_u64 v[246:247], s[18:19], 0, v[76:77]
	v_lshl_add_u64 v[246:247], v[246:247], 0, s[4:5]
	global_load_lds_dwordx4 v[246:247], off
	v_mfma_f32_16x16x32_bf16 v[36:39], v[130:133], v[138:141], v[24:27]
	s_mov_b32 m0, s48
	v_lshl_add_u64 v[246:247], s[18:19], 0, v[70:71]
	v_lshl_add_u64 v[246:247], v[246:247], 0, s[2:3]
	global_load_lds_dwordx4 v[246:247], off
	v_mfma_f32_16x16x32_bf16 v[32:35], v[130:133], v[142:145], v[28:31]
	s_mov_b32 m0, s49
	v_lshl_add_u64 v[246:247], s[18:19], 0, v[78:79]
	v_lshl_add_u64 v[246:247], v[246:247], 0, s[4:5]
	global_load_lds_dwordx4 v[246:247], off
	s_waitcnt lgkmcnt(0)
	v_mfma_f32_16x16x32_bf16 v[28:31], v[0:3], v[114:117], v[118:121]
	s_mov_b32 m0, s51
	v_lshl_add_u64 v[246:247], s[18:19], 0, v[72:73]
	v_lshl_add_u64 v[246:247], v[246:247], 0, s[2:3]
	global_load_lds_dwordx4 v[246:247], off
	v_mfma_f32_16x16x32_bf16 v[24:27], v[0:3], v[134:137], v[122:125]
	s_mov_b32 m0, s52
	v_lshl_add_u64 v[246:247], s[18:19], 0, v[80:81]
	v_lshl_add_u64 v[246:247], v[246:247], 0, s[4:5]
	global_load_lds_dwordx4 v[246:247], off
	v_mfma_f32_16x16x32_bf16 v[16:19], v[0:3], v[138:141], v[126:129]
	v_mfma_f32_16x16x32_bf16 v[12:15], v[0:3], v[142:145], v[82:85]
	v_mfma_f32_16x16x32_bf16 v[4:7], v[8:11], v[114:117], v[86:89]
	v_mfma_f32_16x16x32_bf16 v[0:3], v[8:11], v[134:137], v[94:97]
	v_mfma_f32_16x16x32_bf16 v[20:23], v[8:11], v[138:141], v[110:113]
	v_mfma_f32_16x16x32_bf16 v[8:11], v[8:11], v[142:145], v[90:93]
	s_cmpk_gt_u32 s44, 0xa7f
	s_cselect_b64 s[20:21], -1, 0
	s_and_b64 vcc, exec, s[20:21]
	s_branch .Lge7_k0

; #define GBAR() do { asm volatile("s_waitcnt vmcnt(0) lgkmcnt(0)" ::: "memory"); __builtin_amdgcn_s_barrier(); } while (0)
; template <int EPI, bool GUARD>
; DEVI void gemm_tile(const Params& p, const bf16_t* __restrict__ A, int lda, const bf16_t* __restrict__ Bt, int ldb, int K,
;                           int row_base, int row_lo, int row_hi, int tile_n, int layer, int which, char* lds) {
;     ...
;   const int swz = c16 >> 1;
;   int koff[2];
; #pragma unroll
;   for (int ks = 0; ks < 2; ++ks) koff[ks] = ((ks * 4 + q4) ^ swz) << 4;
;   const int arow = (wr * 64 + c16) * 128, brow = 16384 + (wc * 64 + c16) * 128;
;     ...
;   GISSUE(0, 0); GBAR();
;   for (int k0 = 0; k0 < K; k0 += 128) {
;     GISSUE(k0 + 64, 1);
;     KSTEPS(0);
;     GBAR();
;     if (k0 + 128 < K) GISSUE(k0 + 128, 0);
;     KSTEPS(1);
;     GBAR();
;   }
.Lge7_k0:
	ds_read_b128 v[110:113], v64
	ds_read_b128 v[114:117], v107 offset:16384
	ds_read_b128 v[118:121], v64 offset:2048
	ds_read_b128 v[122:125], v107 offset:18432
	ds_read_b128 v[126:129], v107 offset:20480
	ds_read_b128 v[130:133], v107 offset:22528
	s_waitcnt lgkmcnt(0)
	v_mfma_f32_16x16x32_bf16 v[60:63], v[110:113], v[114:117], v[60:63]
	v_mfma_f32_16x16x32_bf16 v[56:59], v[110:113], v[122:125], v[56:59]
	v_mfma_f32_16x16x32_bf16 v[52:55], v[110:113], v[126:129], v[52:55]
	v_mfma_f32_16x16x32_bf16 v[48:51], v[110:113], v[130:133], v[48:51]
	v_mfma_f32_16x16x32_bf16 v[44:47], v[118:121], v[114:117], v[44:47]
	v_mfma_f32_16x16x32_bf16 v[40:43], v[118:121], v[122:125], v[40:43]
	v_mfma_f32_16x16x32_bf16 v[36:39], v[118:121], v[126:129], v[36:39]
	v_mfma_f32_16x16x32_bf16 v[32:35], v[118:121], v[130:133], v[32:35]
	ds_read_b128 v[110:113], v64 offset:4096
	ds_read_b128 v[118:121], v64 offset:6144
	s_waitcnt lgkmcnt(0)
	v_mfma_f32_16x16x32_bf16 v[134:137], v[110:113], v[114:117], v[28:31]
	v_mfma_f32_16x16x32_bf16 v[138:141], v[110:113], v[122:125], v[24:27]
	v_mfma_f32_16x16x32_bf16 v[142:145], v[110:113], v[126:129], v[16:19]
	v_mfma_f32_16x16x32_bf16 v[110:113], v[110:113], v[130:133], v[12:15]
	s_nop 2
	ds_read_b128 v[12:15], v108
	v_mfma_f32_16x16x32_bf16 v[114:117], v[118:121], v[114:117], v[4:7]
	v_mfma_f32_16x16x32_bf16 v[122:125], v[118:121], v[122:125], v[0:3]
	v_mfma_f32_16x16x32_bf16 v[126:129], v[118:121], v[126:129], v[20:23]
	v_mfma_f32_16x16x32_bf16 v[118:121], v[118:121], v[130:133], v[8:11]
	ds_read_b128 v[130:133], v109 offset:16384
	ds_read_b128 v[28:31], v108 offset:2048
	ds_read_b128 v[146:149], v109 offset:18432
	s_waitcnt lgkmcnt(0)
	v_mfma_f32_16x16x32_bf16 v[0:3], v[12:15], v[130:133], v[60:63]
	v_mfma_f32_16x16x32_bf16 v[4:7], v[12:15], v[146:149], v[56:59]
	s_nop 2
	ds_read_b128 v[56:59], v109 offset:20480
	ds_read_b128 v[60:63], v109 offset:22528
	v_mfma_f32_16x16x32_bf16 v[16:19], v[28:31], v[130:133], v[44:47]
	s_nop 2
	ds_read_b128 v[44:47], v108 offset:4096
	ds_read_b128 v[150:153], v108 offset:6144
	s_waitcnt vmcnt(0) lgkmcnt(0)
	s_barrier
	s_cbranch_vccnz .Lge7_last0
	s_waitcnt lgkmcnt(0)
	v_mfma_f32_16x16x32_bf16 v[8:11], v[12:15], v[56:59], v[52:55]
	s_mov_b32 m0, s36
	v_lshl_add_u64 v[246:247], s[18:19], 0, v[66:67]
	v_lshl_add_u64 v[246:247], v[246:247], 0, s[6:7]
	global_load_lds_dwordx4 v[246:247], off
	v_mfma_f32_16x16x32_bf16 v[12:15], v[12:15], v[60:63], v[48:51]
	s_mov_b32 m0, s37
	v_lshl_add_u64 v[246:247], s[18:19], 0, v[74:75]
	v_lshl_add_u64 v[246:247], v[246:247], 0, s[8:9]
	global_load_lds_dwordx4 v[246:247], off
	v_mfma_f32_16x16x32_bf16 v[20:23], v[28:31], v[146:149], v[40:43]
	s_mov_b32 m0, s38
	v_lshl_add_u64 v[246:247], s[18:19], 0, v[68:69]
	v_lshl_add_u64 v[246:247], v[246:247], 0, s[6:7]
	global_load_lds_dwordx4 v[246:247], off
	v_mfma_f32_16x16x32_bf16 v[24:27], v[28:31], v[56:59], v[36:39]
	s_mov_b32 m0, s39
	v_lshl_add_u64 v[246:247], s[18:19], 0, v[76:77]
	v_lshl_add_u64 v[246:247], v[246:247], 0, s[8:9]
	global_load_lds_dwordx4 v[246:247], off
	v_mfma_f32_16x16x32_bf16 v[28:31], v[28:31], v[60:63], v[32:35]
	s_mov_b32 m0, s40
	v_lshl_add_u64 v[246:247], s[18:19], 0, v[70:71]
	v_lshl_add_u64 v[246:247], v[246:247], 0, s[6:7]
	global_load_lds_dwordx4 v[246:247], off
	v_mfma_f32_16x16x32_bf16 v[32:35], v[44:47], v[130:133], v[134:137]
	s_mov_b32 m0, s41
	v_lshl_add_u64 v[246:247], s[18:19], 0, v[78:79]
	v_lshl_add_u64 v[246:247], v[246:247], 0, s[8:9]
	global_load_lds_dwordx4 v[246:247], off
	v_mfma_f32_16x16x32_bf16 v[36:39], v[44:47], v[146:149], v[138:141]
	s_mov_b32 m0, s42
	v_lshl_add_u64 v[246:247], s[18:19], 0, v[72:73]
	v_lshl_add_u64 v[246:247], v[246:247], 0, s[6:7]
	global_load_lds_dwordx4 v[246:247], off
	v_mfma_f32_16x16x32_bf16 v[40:43], v[44:47], v[56:59], v[142:145]
	s_mov_b32 m0, s43
	v_lshl_add_u64 v[246:247], s[18:19], 0, v[80:81]
	v_lshl_add_u64 v[246:247], v[246:247], 0, s[8:9]
	global_load_lds_dwordx4 v[246:247], off
	v_mfma_f32_16x16x32_bf16 v[44:47], v[44:47], v[60:63], v[110:113]
	v_mfma_f32_16x16x32_bf16 v[48:51], v[150:153], v[130:133], v[114:117]
	v_mfma_f32_16x16x32_bf16 v[52:55], v[150:153], v[146:149], v[122:125]
	v_mfma_f32_16x16x32_bf16 v[56:59], v[150:153], v[56:59], v[126:129]
	v_mfma_f32_16x16x32_bf16 v[60:63], v[150:153], v[60:63], v[118:121]
	s_branch .LBB0_1336
